# reverse M-tile order (pm -> 191-pm) in GEMM2 and fused GEMM9 so HID panels are read most-recently-written first (MALL reuse theory)
# speedup vs baseline: 1.0135x; 1.0135x over previous
;     __host__ __device__ bool next(int i, Unit& u) const {
;         const long L = (long)i * G + c; if (L >= nwg) return false;
;         int wgid = (int)L; { const int q = nwg / NXCD, r = nwg % NXCD, xcd = wgid % NXCD, off = wgid / NXCD; wgid = (xcd < r ? xcd * (q + 1) : r * (q + 1) + (xcd - r) * q) + off; }
;         const int nig = WGM * nN, gid = wgid / nig, fm = gid * WGM, gsz = (nM - fm) < WGM ? (nM - fm) : WGM;
;         u.pm = fm + ((wgid % nig) % gsz); u.pn = (wgid % nig) / gsz; return true;
; template <class Epi, class Sched, bool ALIGN_EPI = false, bool SP2 = false>
; __device__ __forceinline__ void gemm_phase(PG8_LAS unsigned char* lds, const Gemm g, const Sched& S, const Epi& E) {
;     ...
;     if (!S.next(0, cur)) return;
.LBB0_305:
	s_load_dwordx2 s[2:3], s[88:89], 0xa0
	s_waitcnt lgkmcnt(0)
	s_cmp_lt_i32 s2, 3
	s_cselect_b64 s[2:3], -1, 0
	s_add_u32 s48, s92, 0x2d00000
	s_addc_u32 s49, s93, 0
	s_and_b64 s[6:7], s[2:3], s[0:1]
	s_andn2_b64 vcc, exec, s[6:7]
	s_cbranch_vccnz .LBB0_344
	s_cmpk_lt_i32 s33, 0x300
	s_cselect_b64 s[0:1], -1, 0
	s_cmpk_gt_i32 s33, 0x2ff
	v_readfirstlane_b32 s2, v198
	s_cbranch_scc1 .LBB0_308
	s_ashr_i32 s3, s33, 31
	s_lshr_b32 s3, s3, 29
	s_add_i32 s3, s33, s3
	s_ashr_i32 s4, s3, 3
	s_and_b32 s3, s3, -8
	s_sub_i32 s3, s33, s3
	s_cmp_lt_i32 s3, 0
	s_movk_i32 s5, 0x61
	s_cselect_b32 s5, s5, 0x60
	s_mul_i32 s3, s3, s5
	s_add_i32 s3, s3, s4
	s_ashr_i32 s4, s3, 31
	s_lshr_b32 s4, s4, 27
	s_add_i32 s4, s3, s4
	s_ashr_i32 s5, s4, 5
	s_and_b32 s4, s4, 0xffe0
	s_sub_i32 s3, s3, s4
	s_bfe_i32 s4, s3, 0x80000
	s_bfe_u32 s4, s4, 0x3000c
	s_add_i32 s4, s3, s4
	s_bfe_i32 s8, s4, 0x80000
	s_and_b32 s4, s4, 0xf8
	s_sub_i32 s3, s3, s4
	s_lshl_b32 s5, s5, 3
	s_sext_i32_i16 s8, s8
	s_sext_i32_i8 s3, s3
	s_add_i32 s55, s5, s3
	s_sub_i32 s55, 0xbf, s55
	s_ashr_i32 s12, s8, 3

;     __host__ __device__ bool next(int i, Unit& u) const {
;         const long L = (long)i * G + c; if (L >= nwg) return false;
;         int wgid = (int)L; { const int q = nwg / NXCD, r = nwg % NXCD, xcd = wgid % NXCD, off = wgid / NXCD; wgid = (xcd < r ? xcd * (q + 1) : r * (q + 1) + (xcd - r) * q) + off; }
;         const int nig = WGM * nN, gid = wgid / nig, fm = gid * WGM, gsz = (nM - fm) < WGM ? (nM - fm) : WGM;
;         u.pm = fm + ((wgid % nig) % gsz); u.pn = (wgid % nig) / gsz; return true;
; template <class Epi, class Sched, bool ALIGN_EPI = false, bool SP2 = false>
; __device__ __forceinline__ void gemm_phase(PG8_LAS unsigned char* lds, const Gemm g, const Sched& S, const Epi& E) {
;     ...
;         const bool has_next = S.next(ui + 1, nxt);
.LBB0_314:
	s_add_i32 s52, s52, 1
	s_mul_i32 s2, s52, s40
	s_mul_hi_u32 s3, s52, s41
	s_add_i32 s3, s3, s2
	s_mul_i32 s2, s52, s41
	s_add_u32 s2, s2, s33
	s_addc_u32 s3, s3, s42
	v_cmp_gt_i64_e32 vcc, s[2:3], v[158:159]
	v_cmp_lt_i64_e64 s[4:5], s[2:3], v[156:157]
	s_cbranch_vccnz .LBB0_316
	s_ashr_i32 s3, s2, 31
	s_lshr_b32 s3, s3, 29
	s_add_i32 s3, s2, s3
	s_ashr_i32 s18, s3, 3
	s_and_b32 s3, s3, -8
	s_sub_i32 s2, s2, s3
	s_cmp_lt_i32 s2, 0
	s_cselect_b32 s3, s43, 0x60
	s_mul_i32 s2, s2, s3
	s_add_i32 s2, s2, s18
	s_ashr_i32 s3, s2, 31
	s_lshr_b32 s3, s3, 27
	s_add_i32 s3, s2, s3
	s_ashr_i32 s18, s3, 5
	s_lshl_b32 s18, s18, 3
	s_sub_i32 s19, 0xc0, s18
	s_min_i32 s19, s19, 8
	s_abs_i32 s24, s19
	v_cvt_f32_u32_e32 v0, s24
	s_sub_i32 s53, 0, s24
	s_andn2_b32 s3, s3, 31
	s_sub_i32 s2, s2, s3
	v_rcp_iflag_f32_e32 v0, v0
	s_abs_i32 s3, s2
	s_xor_b32 s25, s2, s19
	s_ashr_i32 s25, s25, 31
	v_mul_f32_e32 v0, 0x4f7ffffe, v0
	v_cvt_u32_f32_e32 v0, v0
	s_nop 0
	v_readfirstlane_b32 s54, v0
	s_mul_i32 s53, s53, s54
	s_mul_hi_u32 s53, s54, s53
	s_add_i32 s54, s54, s53
	s_mul_hi_u32 s53, s3, s54
	s_mul_i32 s54, s53, s24
	s_sub_i32 s3, s3, s54
	s_add_i32 s56, s53, 1
	s_sub_i32 s54, s3, s24
	s_cmp_ge_u32 s3, s24
	s_cselect_b32 s53, s56, s53
	s_cselect_b32 s3, s54, s3
	s_add_i32 s54, s53, 1
	s_cmp_ge_u32 s3, s24
	s_cselect_b32 s3, s54, s53
	s_xor_b32 s3, s3, s25
	s_sub_i32 s53, s3, s25
	s_mul_i32 s3, s53, s19
	s_sub_i32 s2, s2, s3
	s_add_i32 s54, s18, s2
	s_sub_i32 s54, 0xbf, s54

;     __host__ __device__ bool next(int i, Unit& u) const {
;         const long L = (long)i * G + c; if (L >= nwg) return false;
;         int wgid = (int)L; { const int q = nwg / NXCD, r = nwg % NXCD, xcd = wgid % NXCD, off = wgid / NXCD; wgid = (xcd < r ? xcd * (q + 1) : r * (q + 1) + (xcd - r) * q) + off; }
;         const int nig = WGM * nN, gid = wgid / nig, fm = gid * WGM, gsz = (nM - fm) < WGM ? (nM - fm) : WGM;
;         u.pm = fm + ((wgid % nig) % gsz); u.pn = (wgid % nig) / gsz; return true;
; template <class Epi, class Sched, bool ALIGN_EPI = false, bool SP2 = false>
; __device__ __forceinline__ void gemm_phase(PG8_LAS unsigned char* lds, const Gemm g, const Sched& S, const Epi& E) {
;     ...
;     if (!S.next(0, cur)) return;
.LBB0_940:
	s_andn2_b64 vcc, exec, s[2:3]
	s_cbranch_vccnz .LBB0_986
	s_cmpk_lt_i32 s33, 0x300
	s_cselect_b64 s[0:1], -1, 0
	s_cmpk_gt_i32 s33, 0x2ff
	v_readfirstlane_b32 s2, v198
	s_cbranch_scc1 .LBB0_943
	s_ashr_i32 s3, s33, 31
	s_lshr_b32 s3, s3, 29
	s_add_i32 s3, s33, s3
	s_ashr_i32 s4, s3, 3
	s_and_b32 s3, s3, -8
	s_sub_i32 s3, s33, s3
	s_cmp_lt_i32 s3, 0
	s_movk_i32 s5, 0x61
	s_cselect_b32 s5, s5, 0x60
	s_mul_i32 s3, s3, s5
	s_add_i32 s3, s3, s4
	s_ashr_i32 s4, s3, 31
	s_lshr_b32 s4, s4, 27
	s_add_i32 s4, s3, s4
	s_ashr_i32 s5, s4, 5
	s_and_b32 s4, s4, 0xffe0
	s_sub_i32 s3, s3, s4
	s_bfe_i32 s4, s3, 0x80000
	s_bfe_u32 s4, s4, 0x3000c
	s_add_i32 s4, s3, s4
	s_bfe_i32 s6, s4, 0x80000
	s_and_b32 s4, s4, 0xf8
	s_sub_i32 s3, s3, s4
	s_lshl_b32 s5, s5, 3
	s_sext_i32_i16 s6, s6
	s_sext_i32_i8 s3, s3
	s_add_i32 s62, s5, s3
	s_sub_i32 s62, 0xbf, s62
	s_ashr_i32 s63, s6, 3

;     __host__ __device__ bool next(int i, Unit& u) const {
;         const long L = (long)i * G + c; if (L >= nwg) return false;
;         int wgid = (int)L; { const int q = nwg / NXCD, r = nwg % NXCD, xcd = wgid % NXCD, off = wgid / NXCD; wgid = (xcd < r ? xcd * (q + 1) : r * (q + 1) + (xcd - r) * q) + off; }
;         const int nig = WGM * nN, gid = wgid / nig, fm = gid * WGM, gsz = (nM - fm) < WGM ? (nM - fm) : WGM;
;         u.pm = fm + ((wgid % nig) % gsz); u.pn = (wgid % nig) / gsz; return true;
; template <class Epi, class Sched, bool ALIGN_EPI = false, bool SP2 = false>
; __device__ __forceinline__ void gemm_phase(PG8_LAS unsigned char* lds, const Gemm g, const Sched& S, const Epi& E) {
;     ...
;         const bool has_next = S.next(ui + 1, nxt);
.LBB0_949:
	s_add_i32 s20, s20, 1
	s_lshl_b64 s[4:5], s[20:21], 8
	s_add_u32 s4, s4, s33
	s_addc_u32 s5, s5, s56
	v_cmp_gt_i64_e32 vcc, s[4:5], v[144:145]
	v_cmp_lt_i64_e64 s[6:7], s[4:5], v[142:143]
	s_cbranch_vccnz .LBB0_951
	s_ashr_i32 s5, s4, 31
	s_lshr_b32 s5, s5, 29
	s_add_i32 s5, s4, s5
	s_ashr_i32 s28, s5, 3
	s_and_b32 s5, s5, -8
	s_sub_i32 s4, s4, s5
	s_cmp_lt_i32 s4, 0
	s_cselect_b32 s5, s57, 0x60
	s_mul_i32 s4, s4, s5
	s_add_i32 s4, s4, s28
	s_ashr_i32 s5, s4, 31
	s_lshr_b32 s5, s5, 27
	s_add_i32 s5, s4, s5
	s_ashr_i32 s28, s5, 5
	s_and_b32 s5, s5, 0xffe0
	s_sub_i32 s4, s4, s5
	s_bfe_i32 s5, s4, 0x80000
	s_bfe_u32 s5, s5, 0x3000c
	s_add_i32 s5, s4, s5
	s_and_b32 s29, s5, 0xf8
	s_sub_i32 s4, s4, s29
	s_lshl_b32 s28, s28, 3
	s_sext_i32_i8 s4, s4
	s_add_i32 s60, s28, s4
	s_sub_i32 s60, 0xbf, s60
	s_bfe_i32 s4, s5, 0x80000
	s_sext_i32_i16 s4, s4
	s_ashr_i32 s61, s4, 3
